# differential attention: V^T fragment prefetch also in the fourth sub-tile body (on v101)
# baseline (speedup 1.0000x reference)
.LBB0_402:
	v_add_u32_e32 v206, v1, v242
	v_add_u32_e32 v207, v1, v243
	ds_read_b128 v[132:135], v206 offset:32768
	ds_read_b128 v[136:139], v207 offset:32768
	ds_read_b128 v[140:143], v206 offset:40960
	ds_read_b128 v[144:147], v207 offset:40960
	ds_read_b128 v[148:151], v206 offset:49152
	ds_read_b128 v[152:155], v207 offset:49152
	ds_read_b128 v[156:159], v206 offset:57344
	ds_read_b128 v[160:163], v207 offset:57344
	v_sub_f32_e32 v2, v246, v3
	v_sub_f32_e32 v3, v80, v2
	v_exp_f32_e32 v3, v3
	v_sub_f32_e32 v5, v81, v2
	v_exp_f32_e32 v5, v5
	v_sub_f32_e32 v6, v82, v2
	v_exp_f32_e32 v6, v6
	v_sub_f32_e32 v7, v83, v2
	v_exp_f32_e32 v7, v7
	v_sub_f32_e32 v8, v84, v2
	v_add_f32_e32 v4, 0, v3
	v_exp_f32_e32 v8, v8
	v_sub_f32_e32 v9, v85, v2
	v_add_f32_e32 v4, v5, v4
	v_exp_f32_e32 v9, v9
	v_sub_f32_e32 v10, v86, v2
	v_add_f32_e32 v4, v6, v4
	v_exp_f32_e32 v10, v10
	v_sub_f32_e32 v11, v87, v2
	v_add_f32_e32 v4, v7, v4
	v_exp_f32_e32 v11, v11
	v_sub_f32_e32 v12, v88, v2
	v_add_f32_e32 v4, v8, v4
	v_exp_f32_e32 v12, v12
	v_sub_f32_e32 v13, v89, v2
	v_add_f32_e32 v4, v9, v4
	v_exp_f32_e32 v13, v13
	v_sub_f32_e32 v14, v90, v2
	v_sub_f32_e32 v15, v91, v2
	v_add_f32_e32 v4, v10, v4
	v_exp_f32_e32 v14, v14
	v_exp_f32_e32 v15, v15
	v_add_f32_e32 v4, v11, v4
	v_add_f32_e32 v4, v12, v4
	v_add_f32_e32 v4, v13, v4
	v_sub_f32_e32 v80, v92, v2
	v_sub_f32_e32 v81, v93, v2
	v_sub_f32_e32 v82, v94, v2
	v_sub_f32_e32 v2, v95, v2
	v_add_f32_e32 v4, v14, v4
	v_exp_f32_e32 v83, v2
	v_cvt_pk_bf16_f32 v2, v3, v5
	v_cvt_pk_bf16_f32 v3, v6, v7
	v_cvt_pk_bf16_f32 v7, v14, v15
	v_cvt_pk_bf16_f32 v5, v10, v11
	v_cvt_pk_bf16_f32 v6, v12, v13
	v_exp_f32_e32 v80, v80
	v_exp_f32_e32 v81, v81
	v_exp_f32_e32 v82, v82
	v_add_f32_e32 v4, v15, v4
	v_add_f32_e32 v4, v80, v4
	v_add_f32_e32 v4, v81, v4
	v_add_f32_e32 v4, v82, v4
	v_add_u32_e32 v1, v1, v243
	v_add_f32_e32 v84, v83, v4
	v_cvt_pk_bf16_f32 v4, v8, v9
	v_cvt_pk_bf16_f32 v8, v80, v81
	v_cvt_pk_bf16_f32 v9, v82, v83
	s_waitcnt lgkmcnt(7)
	v_mfma_f32_32x32x16_bf16 v[64:79], v[132:135], v[2:5], v[64:79]
	v_add_f32_e32 v245, v245, v84
	s_waitcnt lgkmcnt(6)
	v_mfma_f32_32x32x16_bf16 v[64:79], v[136:139], v[6:9], v[64:79]
	s_waitcnt lgkmcnt(5)
	v_mfma_f32_32x32x16_bf16 v[48:63], v[140:143], v[2:5], v[48:63]
	s_waitcnt lgkmcnt(4)
	v_mfma_f32_32x32x16_bf16 v[48:63], v[144:147], v[6:9], v[48:63]
	s_waitcnt lgkmcnt(3)
	v_mfma_f32_32x32x16_bf16 v[32:47], v[148:151], v[2:5], v[32:47]
	s_waitcnt lgkmcnt(2)
	v_mfma_f32_32x32x16_bf16 v[32:47], v[152:155], v[6:9], v[32:47]
	s_waitcnt lgkmcnt(1)
	v_mfma_f32_32x32x16_bf16 v[16:31], v[156:159], v[2:5], v[16:31]
	s_waitcnt lgkmcnt(0)
	v_mfma_f32_32x32x16_bf16 v[16:31], v[160:163], v[6:9], v[16:31]
	s_andn2_b64 vcc, exec, s[46:47]
	s_cbranch_vccz .LBB0_310
